# out GEMM K-loop also rewritten software-pipelined (in-place fragment reload, LDS reads + LDS-DMA between MFMAs, no stagger), on top of the fp6 loop
# baseline (speedup 1.0000x reference)
.LBB0_808:
	s_add_u32 s33, s92, 0x13000000
	s_addc_u32 s40, s93, 0
	s_add_u32 s41, s92, 0x7000000
	s_addc_u32 s42, s93, 0
	s_ashr_i32 s2, s4, 3
	s_add_i32 s2, s6, s2
	s_ashr_i32 s3, s2, 31
	s_lshr_b32 s3, s3, 25
	s_add_i32 s3, s2, s3
	s_ashr_i32 s4, s3, 7
	s_and_b32 s3, s3, 0xffffff80
	s_sub_i32 s2, s2, s3
	s_bfe_i32 s3, s2, 0x80000
	s_bfe_u32 s3, s3, 0x3000c
	s_add_i32 s3, s2, s3
	s_lshl_b32 s6, s4, 3
	s_bfe_i32 s4, s3, 0x80000
	s_and_b32 s3, s3, 0xf8
	s_sub_i32 s2, s2, s3
	s_sext_i32_i16 s4, s4
	s_sext_i32_i8 s2, s2
	s_lshr_b32 s4, s4, 3
	s_add_i32 s28, s6, s2
	s_lshr_b32 s9, s5, 6
	s_ashr_i32 s29, s28, 31
	s_bfe_i64 s[6:7], s[4:5], 0x100000
	s_lshr_b32 s8, s5, 8
	s_lshl_b32 s43, s9, 10
	s_lshl_b64 s[2:3], s[28:29], 21
	s_lshl_b64 s[6:7], s[6:7], 21
	v_lshlrev_b32_e32 v1, 4, v0
	s_add_u32 s34, s41, s6
	v_and_b32_e32 v2, 0x3f0, v1
	s_addc_u32 s35, s42, s7
	s_add_i32 s29, s43, 0
	v_or_b32_e32 v134, s43, v2
	s_add_i32 m0, s29, 0x10000
	v_add_u32_e32 v136, 0x2000, v134
	global_load_lds_dwordx4 v134, s[34:35]
	s_add_i32 m0, s29, 0x12000
	s_add_u32 s6, s34, 0x100000
	global_load_lds_dwordx4 v136, s[34:35]
	s_addc_u32 s7, s35, 0
	s_add_i32 m0, s29, 0x14000
	v_mov_b32_e32 v135, 0
	global_load_lds_dwordx4 v134, s[6:7]
	s_add_i32 m0, s29, 0x16000
	s_add_u32 s30, s33, s2
	s_addc_u32 s31, s40, s3
	s_add_i32 s44, s29, 0x2000
	global_load_lds_dwordx4 v136, s[6:7]
	s_mov_b32 m0, s29
	s_add_u32 s2, s30, 0x100000
	global_load_lds_dwordx4 v134, s[30:31]
	s_mov_b32 m0, s44
	s_addc_u32 s3, s31, 0
	s_add_i32 s45, s29, 0x4000
	global_load_lds_dwordx4 v136, s[30:31]
	s_mov_b32 m0, s45
	s_add_i32 s46, s29, 0x6000
	global_load_lds_dwordx4 v134, s[2:3]
	s_mov_b32 m0, s46
	s_cmp_eq_u32 s8, 1
	global_load_lds_dwordx4 v136, s[2:3]
	s_mov_b32 s47, 0
	s_cselect_b64 s[2:3], -1, 0
	s_cmp_lg_u32 s8, 1
	v_mov_b32_e32 v137, v135
	s_cbranch_scc1 .LBB0_810
	s_nop 0
.LBB0_810:
	s_add_u32 s6, s92, 0x53800000
	s_addc_u32 s7, s93, 0
	s_lshl_b32 s9, s9, 5
	s_and_b32 s14, s9, 0x60
	s_lshl_b32 s10, s8, 13
	s_lshl_b32 s9, s14, 7
	s_add_u32 s12, s34, 0x4000
	s_addc_u32 s13, s35, 0
	s_add_i32 m0, s29, 0x18000
	v_lshl_add_u64 v[4:5], s[12:13], 0, v[134:135]
	s_waitcnt vmcnt(2)
	s_barrier
	global_load_lds_dwordx4 v[4:5], off
	s_add_i32 m0, s29, 0x1a000
	v_lshl_add_u64 v[4:5], s[12:13], 0, v[136:137]
	s_add_u32 s12, s30, 0x4000
	s_addc_u32 s13, s31, 0
	s_add_i32 s48, s29, 0x8000
	global_load_lds_dwordx4 v[4:5], off
	v_lshl_add_u64 v[4:5], s[12:13], 0, v[134:135]
	s_mov_b32 m0, s48
	s_add_i32 s49, s29, 0xa000
	global_load_lds_dwordx4 v[4:5], off
	v_lshl_add_u64 v[4:5], s[12:13], 0, v[136:137]
	s_add_u32 s12, s34, 0x104000
	s_mov_b32 m0, s49
	s_addc_u32 s13, s35, 0
	global_load_lds_dwordx4 v[4:5], off
	s_add_i32 m0, s29, 0x1c000
	v_lshl_add_u64 v[4:5], s[12:13], 0, v[134:135]
	global_load_lds_dwordx4 v[4:5], off
	v_lshl_add_u64 v[4:5], s[12:13], 0, v[136:137]
	s_add_i32 m0, s29, 0x1e000
	v_lshrrev_b32_e32 v1, 1, v0
	global_load_lds_dwordx4 v[4:5], off
	v_and_b32_e32 v4, 24, v1
	s_sext_i32_i8 s53, s4
	v_and_b32_e32 v3, 15, v0
	v_lshlrev_b32_e32 v5, 1, v4
	v_lshlrev_b32_e32 v7, 6, v0
	s_movk_i32 s4, 0x3c0
	v_lshl_or_b32 v1, s8, 6, v3
	v_lshl_or_b32 v3, v3, 6, v5
	v_and_b32_e32 v6, 32, v179
	v_and_or_b32 v5, v7, s4, v5
	s_waitcnt vmcnt(6)
	s_cmpk_lt_u32 s5, 0x100
	v_bitop3_b32 v3, v3, s10, v6 bitop3:0xde
	v_bitop3_b32 v152, s9, v5, v6 bitop3:0xf6
	s_cselect_b64 s[8:9], -1, 0
	v_readlane_b32 s4, v249, 34
	v_add_u32_e32 v138, s43, v2
	s_add_i32 s51, 0, 0x10000
	s_add_i32 s52, 0, 0x14000
	s_ashr_i32 s50, s4, 31
	v_or_b32_e32 v153, s14, v4
	v_mov_b32_e32 v139, v135
	v_add_u32_e32 v140, 0x2000, v138
	v_mov_b32_e32 v141, v135
	v_mov_b64_e32 v[142:143], 0x200
	v_mov_b64_e32 v[144:145], 0x1ff
	v_add_u32_e32 v154, s51, v152
	v_add_u32_e32 v155, s52, v152
	v_add_u32_e32 v156, 0, v3
	s_mov_b32 s10, 0x3fb504f3
	s_mov_b64 s[12:13], 0x200000
	s_mov_b64 s[14:15], 0x240000
	s_mov_b64 s[16:17], 0x280000
	s_mov_b64 s[18:19], 0x2c0000
	s_barrier
	v_readlane_b32 s5, v249, 35
	s_mov_b32 s32, 1
	s_branch .LBB0_813

.LBB0_820:
	s_cmp_eq_u32 s32, 0
	s_cbranch_scc1 .Lb16_rd_o0
	s_add_i32 m0, s29, 0xc000
	s_nop 0
	global_load_lds_dwordx4 v134, s[30:31]
	s_add_i32 m0, s29, 0xe000
	s_nop 0
	global_load_lds_dwordx4 v136, s[30:31]
	s_mov_b32 s32, 0
.Lb16_rd_o0:
	ds_read_b128 v[184:187], v156
	ds_read_b128 v[188:191], v156 offset:1024
	ds_read_b128 v[200:203], v156 offset:2048
	ds_read_b128 v[204:207], v156 offset:3072
	ds_read_b128 v[208:211], v156 offset:4096
	ds_read_b128 v[212:215], v156 offset:5120
	ds_read_b128 v[216:219], v156 offset:6144
	ds_read_b128 v[220:223], v156 offset:7168
	ds_read_b128 v[130:133], v154
	ds_read_b128 v[146:149], v154 offset:1024
	ds_read_b128 v[158:161], v154 offset:2048
	ds_read_b128 v[162:165], v154 offset:3072
	ds_read_b128 v[166:169], v154 offset:16384
	ds_read_b128 v[170:173], v154 offset:17408
	ds_read_b128 v[174:177], v154 offset:18432
	ds_read_b128 v[180:183], v154 offset:19456
	s_waitcnt lgkmcnt(0)
	s_barrier
.Lb16_top_o0:
	s_add_u32 s34, s30, 0xfff04000
	s_addc_u32 s35, s31, -1
	s_cmp_eq_u32 s58, 60
	s_cselect_b32 s38, s54, s34
	s_cselect_b32 s39, s23, s35
	s_cselect_b32 s36, s55, s56
	s_cselect_b32 s37, s21, s57
	s_add_u32 s34, s36, 0x100000
	s_addc_u32 s35, s37, 0
	s_add_i32 m0, s29, 0x0
	v_mfma_f32_16x16x32_bf16 v[126:129], v[130:133], v[184:187], v[126:129]
	global_load_lds_dwordx4 v134, s[38:39]
	v_mfma_f32_16x16x32_bf16 v[126:129], v[146:149], v[188:191], v[126:129]
	v_mfma_f32_16x16x32_bf16 v[122:125], v[158:161], v[184:187], v[122:125]
	ds_read_b128 v[224:227], v156 offset:22528
	v_mfma_f32_16x16x32_bf16 v[122:125], v[162:165], v[188:191], v[122:125]
	v_mfma_f32_16x16x32_bf16 v[106:109], v[166:169], v[184:187], v[106:109]
	ds_read_b128 v[228:231], v156 offset:23552
	v_mfma_f32_16x16x32_bf16 v[106:109], v[170:173], v[188:191], v[106:109]
	s_add_i32 m0, s29, 0x2000
	v_mfma_f32_16x16x32_bf16 v[102:105], v[174:177], v[184:187], v[102:105]
	global_load_lds_dwordx4 v136, s[38:39]
	v_mfma_f32_16x16x32_bf16 v[102:105], v[180:183], v[188:191], v[102:105]
	ds_read_b128 v[184:187], v156 offset:16384
	ds_read_b128 v[188:191], v156 offset:17408
	s_add_i32 m0, s29, 0x10000
	v_mfma_f32_16x16x32_bf16 v[118:121], v[130:133], v[200:203], v[118:121]
	global_load_lds_dwordx4 v134, s[36:37]
	v_mfma_f32_16x16x32_bf16 v[118:121], v[146:149], v[204:207], v[118:121]
	s_add_i32 m0, s29, 0x12000
	v_mfma_f32_16x16x32_bf16 v[114:117], v[158:161], v[200:203], v[114:117]
	global_load_lds_dwordx4 v136, s[36:37]
	v_mfma_f32_16x16x32_bf16 v[114:117], v[162:165], v[204:207], v[114:117]
	s_add_i32 m0, s29, 0x14000
	v_mfma_f32_16x16x32_bf16 v[94:97], v[166:169], v[200:203], v[94:97]
	global_load_lds_dwordx4 v134, s[34:35]
	v_mfma_f32_16x16x32_bf16 v[94:97], v[170:173], v[204:207], v[94:97]
	s_add_i32 m0, s29, 0x16000
	v_mfma_f32_16x16x32_bf16 v[90:93], v[174:177], v[200:203], v[90:93]
	global_load_lds_dwordx4 v136, s[34:35]
	v_mfma_f32_16x16x32_bf16 v[90:93], v[180:183], v[204:207], v[90:93]
	ds_read_b128 v[200:203], v156 offset:18432
	ds_read_b128 v[204:207], v156 offset:19456
	v_mfma_f32_16x16x32_bf16 v[110:113], v[130:133], v[208:211], v[110:113]
	v_mfma_f32_16x16x32_bf16 v[110:113], v[146:149], v[212:215], v[110:113]
	v_mfma_f32_16x16x32_bf16 v[98:101], v[158:161], v[208:211], v[98:101]
	v_mfma_f32_16x16x32_bf16 v[98:101], v[162:165], v[212:215], v[98:101]
	v_mfma_f32_16x16x32_bf16 v[82:85], v[166:169], v[208:211], v[82:85]
	v_mfma_f32_16x16x32_bf16 v[82:85], v[170:173], v[212:215], v[82:85]
	v_mfma_f32_16x16x32_bf16 v[74:77], v[174:177], v[208:211], v[74:77]
	v_mfma_f32_16x16x32_bf16 v[74:77], v[180:183], v[212:215], v[74:77]
	ds_read_b128 v[208:211], v156 offset:20480
	ds_read_b128 v[212:215], v156 offset:21504
	v_mfma_f32_16x16x32_bf16 v[86:89], v[130:133], v[216:219], v[86:89]
	v_mfma_f32_16x16x32_bf16 v[86:89], v[146:149], v[220:223], v[86:89]
	v_mfma_f32_16x16x32_bf16 v[78:81], v[158:161], v[216:219], v[78:81]
	v_mfma_f32_16x16x32_bf16 v[78:81], v[162:165], v[220:223], v[78:81]
	v_mfma_f32_16x16x32_bf16 v[70:73], v[166:169], v[216:219], v[70:73]
	v_mfma_f32_16x16x32_bf16 v[70:73], v[170:173], v[220:223], v[70:73]
	v_mfma_f32_16x16x32_bf16 v[66:69], v[174:177], v[216:219], v[66:69]
	v_mfma_f32_16x16x32_bf16 v[66:69], v[180:183], v[220:223], v[66:69]
	s_waitcnt vmcnt(8)
	s_waitcnt lgkmcnt(0)
	s_barrier
	s_add_u32 s34, s38, 0x100000
	s_addc_u32 s35, s39, 0
	s_add_i32 m0, s29, 0x4000
	v_mfma_f32_16x16x32_bf16 v[62:65], v[130:133], v[184:187], v[62:65]
	global_load_lds_dwordx4 v134, s[34:35]
	v_mfma_f32_16x16x32_bf16 v[62:65], v[146:149], v[188:191], v[62:65]
	v_mfma_f32_16x16x32_bf16 v[58:61], v[158:161], v[184:187], v[58:61]
	ds_read_b128 v[216:219], v156 offset:38912
	v_mfma_f32_16x16x32_bf16 v[58:61], v[162:165], v[188:191], v[58:61]
	v_mfma_f32_16x16x32_bf16 v[46:49], v[166:169], v[184:187], v[46:49]
	ds_read_b128 v[220:223], v156 offset:39936
	v_mfma_f32_16x16x32_bf16 v[46:49], v[170:173], v[188:191], v[46:49]
	s_add_i32 m0, s29, 0x6000
	v_mfma_f32_16x16x32_bf16 v[42:45], v[174:177], v[184:187], v[42:45]
	global_load_lds_dwordx4 v136, s[34:35]
	v_mfma_f32_16x16x32_bf16 v[42:45], v[180:183], v[188:191], v[42:45]
	ds_read_b128 v[184:187], v156 offset:32768
	ds_read_b128 v[188:191], v156 offset:33792
	v_mfma_f32_16x16x32_bf16 v[54:57], v[130:133], v[200:203], v[54:57]
	ds_read_b128 v[232:235], v154 offset:49152
	v_mfma_f32_16x16x32_bf16 v[54:57], v[146:149], v[204:207], v[54:57]
	v_mfma_f32_16x16x32_bf16 v[50:53], v[158:161], v[200:203], v[50:53]
	ds_read_b128 v[236:239], v154 offset:50176
	v_mfma_f32_16x16x32_bf16 v[50:53], v[162:165], v[204:207], v[50:53]
	v_mfma_f32_16x16x32_bf16 v[34:37], v[166:169], v[200:203], v[34:37]
	ds_read_b128 v[240:243], v154 offset:51200
	v_mfma_f32_16x16x32_bf16 v[34:37], v[170:173], v[204:207], v[34:37]
	v_mfma_f32_16x16x32_bf16 v[26:29], v[174:177], v[200:203], v[26:29]
	ds_read_b128 v[244:247], v154 offset:52224
	v_mfma_f32_16x16x32_bf16 v[26:29], v[180:183], v[204:207], v[26:29]
	ds_read_b128 v[200:203], v156 offset:34816
	ds_read_b128 v[204:207], v156 offset:35840
	v_mfma_f32_16x16x32_bf16 v[38:41], v[130:133], v[208:211], v[38:41]
	v_mfma_f32_16x16x32_bf16 v[38:41], v[146:149], v[212:215], v[38:41]
	v_mfma_f32_16x16x32_bf16 v[30:33], v[158:161], v[208:211], v[30:33]
	v_mfma_f32_16x16x32_bf16 v[30:33], v[162:165], v[212:215], v[30:33]
	v_mfma_f32_16x16x32_bf16 v[18:21], v[166:169], v[208:211], v[18:21]
	v_mfma_f32_16x16x32_bf16 v[18:21], v[170:173], v[212:215], v[18:21]
	v_mfma_f32_16x16x32_bf16 v[10:13], v[174:177], v[208:211], v[10:13]
	v_mfma_f32_16x16x32_bf16 v[10:13], v[180:183], v[212:215], v[10:13]
	ds_read_b128 v[208:211], v156 offset:36864
	ds_read_b128 v[212:215], v156 offset:37888
	v_mfma_f32_16x16x32_bf16 v[22:25], v[130:133], v[224:227], v[22:25]
	v_mfma_f32_16x16x32_bf16 v[22:25], v[146:149], v[228:231], v[22:25]
	ds_read_b128 v[130:133], v154 offset:32768
	ds_read_b128 v[146:149], v154 offset:33792
	v_mfma_f32_16x16x32_bf16 v[14:17], v[158:161], v[224:227], v[14:17]
	v_mfma_f32_16x16x32_bf16 v[14:17], v[162:165], v[228:231], v[14:17]
	ds_read_b128 v[158:161], v154 offset:34816
	ds_read_b128 v[162:165], v154 offset:35840
	v_mfma_f32_16x16x32_bf16 v[6:9], v[166:169], v[224:227], v[6:9]
	v_mfma_f32_16x16x32_bf16 v[6:9], v[170:173], v[228:231], v[6:9]
	v_mfma_f32_16x16x32_bf16 v[2:5], v[174:177], v[224:227], v[2:5]
	v_mfma_f32_16x16x32_bf16 v[2:5], v[180:183], v[228:231], v[2:5]
	s_waitcnt vmcnt(8)
	s_waitcnt lgkmcnt(0)
	s_barrier
	s_add_u32 s38, s38, 0x4000
	s_addc_u32 s39, s39, 0
	s_add_u32 s36, s36, 0x4000
	s_addc_u32 s37, s37, 0
	s_add_u32 s34, s36, 0x100000
	s_addc_u32 s35, s37, 0
	s_add_i32 m0, s29, 0x8000
	v_mfma_f32_16x16x32_bf16 v[126:129], v[130:133], v[184:187], v[126:129]
	global_load_lds_dwordx4 v134, s[38:39]
	v_mfma_f32_16x16x32_bf16 v[126:129], v[146:149], v[188:191], v[126:129]
	v_mfma_f32_16x16x32_bf16 v[122:125], v[158:161], v[184:187], v[122:125]
	ds_read_b128 v[224:227], v156 offset:55296
	v_mfma_f32_16x16x32_bf16 v[122:125], v[162:165], v[188:191], v[122:125]
	v_mfma_f32_16x16x32_bf16 v[106:109], v[232:235], v[184:187], v[106:109]
	ds_read_b128 v[228:231], v156 offset:56320
	v_mfma_f32_16x16x32_bf16 v[106:109], v[236:239], v[188:191], v[106:109]
	s_add_i32 m0, s29, 0xa000
	v_mfma_f32_16x16x32_bf16 v[102:105], v[240:243], v[184:187], v[102:105]
	global_load_lds_dwordx4 v136, s[38:39]
	v_mfma_f32_16x16x32_bf16 v[102:105], v[244:247], v[188:191], v[102:105]
	ds_read_b128 v[184:187], v156 offset:49152
	ds_read_b128 v[188:191], v156 offset:50176
	s_add_i32 m0, s29, 0x18000
	v_mfma_f32_16x16x32_bf16 v[118:121], v[130:133], v[200:203], v[118:121]
	global_load_lds_dwordx4 v134, s[36:37]
	v_mfma_f32_16x16x32_bf16 v[118:121], v[146:149], v[204:207], v[118:121]
	s_add_i32 m0, s29, 0x1a000
	v_mfma_f32_16x16x32_bf16 v[114:117], v[158:161], v[200:203], v[114:117]
	global_load_lds_dwordx4 v136, s[36:37]
	v_mfma_f32_16x16x32_bf16 v[114:117], v[162:165], v[204:207], v[114:117]
	s_add_i32 m0, s29, 0x1c000
	v_mfma_f32_16x16x32_bf16 v[94:97], v[232:235], v[200:203], v[94:97]
	global_load_lds_dwordx4 v134, s[34:35]
	v_mfma_f32_16x16x32_bf16 v[94:97], v[236:239], v[204:207], v[94:97]
	s_add_i32 m0, s29, 0x1e000
	v_mfma_f32_16x16x32_bf16 v[90:93], v[240:243], v[200:203], v[90:93]
	global_load_lds_dwordx4 v136, s[34:35]
	v_mfma_f32_16x16x32_bf16 v[90:93], v[244:247], v[204:207], v[90:93]
	ds_read_b128 v[200:203], v156 offset:51200
	ds_read_b128 v[204:207], v156 offset:52224
	v_mfma_f32_16x16x32_bf16 v[110:113], v[130:133], v[208:211], v[110:113]
	v_mfma_f32_16x16x32_bf16 v[110:113], v[146:149], v[212:215], v[110:113]
	v_mfma_f32_16x16x32_bf16 v[98:101], v[158:161], v[208:211], v[98:101]
	v_mfma_f32_16x16x32_bf16 v[98:101], v[162:165], v[212:215], v[98:101]
	v_mfma_f32_16x16x32_bf16 v[82:85], v[232:235], v[208:211], v[82:85]
	v_mfma_f32_16x16x32_bf16 v[82:85], v[236:239], v[212:215], v[82:85]
	v_mfma_f32_16x16x32_bf16 v[74:77], v[240:243], v[208:211], v[74:77]
	v_mfma_f32_16x16x32_bf16 v[74:77], v[244:247], v[212:215], v[74:77]
	ds_read_b128 v[208:211], v156 offset:53248
	ds_read_b128 v[212:215], v156 offset:54272
	v_mfma_f32_16x16x32_bf16 v[86:89], v[130:133], v[216:219], v[86:89]
	v_mfma_f32_16x16x32_bf16 v[86:89], v[146:149], v[220:223], v[86:89]
	v_mfma_f32_16x16x32_bf16 v[78:81], v[158:161], v[216:219], v[78:81]
	v_mfma_f32_16x16x32_bf16 v[78:81], v[162:165], v[220:223], v[78:81]
	v_mfma_f32_16x16x32_bf16 v[70:73], v[232:235], v[216:219], v[70:73]
	v_mfma_f32_16x16x32_bf16 v[70:73], v[236:239], v[220:223], v[70:73]
	v_mfma_f32_16x16x32_bf16 v[66:69], v[240:243], v[216:219], v[66:69]
	v_mfma_f32_16x16x32_bf16 v[66:69], v[244:247], v[220:223], v[66:69]
	s_waitcnt vmcnt(8)
	s_waitcnt lgkmcnt(0)
	s_barrier
	s_add_u32 s34, s38, 0x100000
	s_addc_u32 s35, s39, 0
	s_add_i32 m0, s29, 0xc000
	v_mfma_f32_16x16x32_bf16 v[62:65], v[130:133], v[184:187], v[62:65]
	global_load_lds_dwordx4 v134, s[34:35]
	v_mfma_f32_16x16x32_bf16 v[62:65], v[146:149], v[188:191], v[62:65]
	v_mfma_f32_16x16x32_bf16 v[58:61], v[158:161], v[184:187], v[58:61]
	ds_read_b128 v[216:219], v156 offset:6144
	v_mfma_f32_16x16x32_bf16 v[58:61], v[162:165], v[188:191], v[58:61]
	v_mfma_f32_16x16x32_bf16 v[46:49], v[232:235], v[184:187], v[46:49]
	ds_read_b128 v[220:223], v156 offset:7168
	v_mfma_f32_16x16x32_bf16 v[46:49], v[236:239], v[188:191], v[46:49]
	s_add_i32 m0, s29, 0xe000
	v_mfma_f32_16x16x32_bf16 v[42:45], v[240:243], v[184:187], v[42:45]
	global_load_lds_dwordx4 v136, s[34:35]
	v_mfma_f32_16x16x32_bf16 v[42:45], v[244:247], v[188:191], v[42:45]
	ds_read_b128 v[184:187], v156
	ds_read_b128 v[188:191], v156 offset:1024
	v_mfma_f32_16x16x32_bf16 v[54:57], v[130:133], v[200:203], v[54:57]
	ds_read_b128 v[166:169], v154 offset:16384
	v_mfma_f32_16x16x32_bf16 v[54:57], v[146:149], v[204:207], v[54:57]
	v_mfma_f32_16x16x32_bf16 v[50:53], v[158:161], v[200:203], v[50:53]
	ds_read_b128 v[170:173], v154 offset:17408
	v_mfma_f32_16x16x32_bf16 v[50:53], v[162:165], v[204:207], v[50:53]
	v_mfma_f32_16x16x32_bf16 v[34:37], v[232:235], v[200:203], v[34:37]
	ds_read_b128 v[174:177], v154 offset:18432
	v_mfma_f32_16x16x32_bf16 v[34:37], v[236:239], v[204:207], v[34:37]
	v_mfma_f32_16x16x32_bf16 v[26:29], v[240:243], v[200:203], v[26:29]
	ds_read_b128 v[180:183], v154 offset:19456
	v_mfma_f32_16x16x32_bf16 v[26:29], v[244:247], v[204:207], v[26:29]
	ds_read_b128 v[200:203], v156 offset:2048
	ds_read_b128 v[204:207], v156 offset:3072
	v_mfma_f32_16x16x32_bf16 v[38:41], v[130:133], v[208:211], v[38:41]
	v_mfma_f32_16x16x32_bf16 v[38:41], v[146:149], v[212:215], v[38:41]
	v_mfma_f32_16x16x32_bf16 v[30:33], v[158:161], v[208:211], v[30:33]
	v_mfma_f32_16x16x32_bf16 v[30:33], v[162:165], v[212:215], v[30:33]
	v_mfma_f32_16x16x32_bf16 v[18:21], v[232:235], v[208:211], v[18:21]
	v_mfma_f32_16x16x32_bf16 v[18:21], v[236:239], v[212:215], v[18:21]
	v_mfma_f32_16x16x32_bf16 v[10:13], v[240:243], v[208:211], v[10:13]
	v_mfma_f32_16x16x32_bf16 v[10:13], v[244:247], v[212:215], v[10:13]
	ds_read_b128 v[208:211], v156 offset:4096
	ds_read_b128 v[212:215], v156 offset:5120
	v_mfma_f32_16x16x32_bf16 v[22:25], v[130:133], v[224:227], v[22:25]
	v_mfma_f32_16x16x32_bf16 v[22:25], v[146:149], v[228:231], v[22:25]
	ds_read_b128 v[130:133], v154
	ds_read_b128 v[146:149], v154 offset:1024
	v_mfma_f32_16x16x32_bf16 v[14:17], v[158:161], v[224:227], v[14:17]
	v_mfma_f32_16x16x32_bf16 v[14:17], v[162:165], v[228:231], v[14:17]
	ds_read_b128 v[158:161], v154 offset:2048
	ds_read_b128 v[162:165], v154 offset:3072
	v_mfma_f32_16x16x32_bf16 v[6:9], v[232:235], v[224:227], v[6:9]
	v_mfma_f32_16x16x32_bf16 v[6:9], v[236:239], v[228:231], v[6:9]
	v_mfma_f32_16x16x32_bf16 v[2:5], v[240:243], v[224:227], v[2:5]
	v_mfma_f32_16x16x32_bf16 v[2:5], v[244:247], v[228:231], v[2:5]
	s_waitcnt vmcnt(8)
	s_waitcnt lgkmcnt(0)
	s_barrier
	s_add_i32 s58, s58, 2
	s_add_u32 s30, s30, 0x8000
	s_addc_u32 s31, s31, 0
	s_add_u32 s56, s56, 0x8000
	s_addc_u32 s57, s57, 0
	s_cmp_gt_u32 s58, 61
	s_cbranch_scc0 .Lb16_top_o0
	s_nop 7
	s_and_b64 vcc, exec, s[8:9]
	s_cbranch_vccz .LBB0_823
	s_nop 0
.LBB0_823:
	v_lshl_or_b32 v132, s53, 8, v153
	v_lshl_add_u32 v130, s28, 8, v1
	v_ashrrev_i32_e32 v133, 31, v132
	v_readlane_b32 s56, v249, 0
	v_lshlrev_b64 v[146:147], 2, v[132:133]
	v_readlane_b32 s57, v249, 1
	v_ashrrev_i32_e32 v131, 31, v130
	v_lshlrev_b64 v[150:151], 14, v[130:131]
	v_lshl_add_u64 v[148:149], s[56:57], 0, v[146:147]
	v_lshl_add_u64 v[132:133], v[148:149], 0, v[150:151]
	global_load_dwordx4 v[158:161], v[132:133], off offset:16
	global_load_dwordx4 v[162:165], v[132:133], off
	global_load_dwordx4 v[166:169], v[132:133], off offset:528
	global_load_dwordx4 v[170:173], v[132:133], off offset:512
	v_or_b32_e32 v132, 16, v130
	v_ashrrev_i32_e32 v133, 31, v132
	v_lshlrev_b64 v[228:229], 14, v[132:133]
	v_lshl_add_u64 v[132:133], v[148:149], 0, v[228:229]
	global_load_dwordx4 v[174:177], v[132:133], off offset:16
	global_load_dwordx4 v[180:183], v[132:133], off
	global_load_dwordx4 v[184:187], v[132:133], off offset:528
	global_load_dwordx4 v[188:191], v[132:133], off offset:512
	v_or_b32_e32 v132, 32, v130
	v_ashrrev_i32_e32 v133, 31, v132
	v_or_b32_e32 v130, 48, v130
	v_lshlrev_b64 v[230:231], 14, v[132:133]
	v_ashrrev_i32_e32 v131, 31, v130
	v_lshl_add_u64 v[132:133], v[148:149], 0, v[230:231]
	v_lshlrev_b64 v[232:233], 14, v[130:131]
	global_load_dwordx4 v[200:203], v[132:133], off offset:16
	global_load_dwordx4 v[204:207], v[132:133], off
	global_load_dwordx4 v[208:211], v[132:133], off offset:528
	global_load_dwordx4 v[212:215], v[132:133], off offset:512
	v_lshl_add_u64 v[130:131], v[148:149], 0, v[232:233]
	global_load_dwordx4 v[216:219], v[130:131], off
	global_load_dwordx4 v[220:223], v[130:131], off offset:16
	global_load_dwordx4 v[224:227], v[130:131], off offset:512
	s_nop 0
	global_load_dwordx4 v[130:133], v[130:131], off offset:528
	v_lshl_add_u64 v[234:235], s[6:7], 0, v[150:151]
	v_lshl_add_u64 v[230:231], s[6:7], 0, v[230:231]
	v_lshl_add_u64 v[234:235], v[234:235], 0, v[146:147]
	v_lshl_add_u64 v[228:229], s[6:7], 0, v[228:229]
	v_lshl_add_u64 v[230:231], v[230:231], 0, v[146:147]
	v_lshl_add_u64 v[228:229], v[228:229], 0, v[146:147]
	s_andn2_b64 vcc, exec, s[4:5]
	s_mov_b64 s[4:5], -1
	v_readlane_b32 s58, v249, 2
	v_readlane_b32 s59, v249, 3
	v_readlane_b32 s60, v249, 4
	v_readlane_b32 s61, v249, 5
	v_readlane_b32 s62, v249, 6
	v_readlane_b32 s63, v249, 7
	v_readlane_b32 s64, v249, 8
	v_readlane_b32 s65, v249, 9
	v_readlane_b32 s66, v249, 10
	v_readlane_b32 s67, v249, 11
	v_readlane_b32 s68, v249, 12
	v_readlane_b32 s69, v249, 13
	v_readlane_b32 s70, v249, 14
	v_readlane_b32 s71, v249, 15
	s_waitcnt vmcnt(0)
	s_nop 0
	v_pk_fma_f32 v[128:129], v[164:165], s[10:11], v[128:129] op_sel_hi:[1,0,1]
	v_pk_fma_f32 v[126:127], v[162:163], s[10:11], v[126:127] op_sel_hi:[1,0,1]
	v_pk_fma_f32 v[84:85], v[214:215], s[10:11], v[84:85] op_sel_hi:[1,0,1]
	v_pk_fma_f32 v[82:83], v[212:213], s[10:11], v[82:83] op_sel_hi:[1,0,1]
	v_pk_fma_f32 v[124:125], v[160:161], s[10:11], v[124:125] op_sel_hi:[1,0,1]
	v_pk_fma_f32 v[122:123], v[158:159], s[10:11], v[122:123] op_sel_hi:[1,0,1]
	v_pk_fma_f32 v[108:109], v[172:173], s[10:11], v[108:109] op_sel_hi:[1,0,1]
	v_pk_fma_f32 v[106:107], v[170:171], s[10:11], v[106:107] op_sel_hi:[1,0,1]
	v_pk_fma_f32 v[104:105], v[168:169], s[10:11], v[104:105] op_sel_hi:[1,0,1]
	v_pk_fma_f32 v[102:103], v[166:167], s[10:11], v[102:103] op_sel_hi:[1,0,1]
	v_pk_fma_f32 v[120:121], v[182:183], s[10:11], v[120:121] op_sel_hi:[1,0,1]
	v_pk_fma_f32 v[118:119], v[180:181], s[10:11], v[118:119] op_sel_hi:[1,0,1]
	v_pk_fma_f32 v[116:117], v[176:177], s[10:11], v[116:117] op_sel_hi:[1,0,1]
	v_pk_fma_f32 v[114:115], v[174:175], s[10:11], v[114:115] op_sel_hi:[1,0,1]
	v_pk_fma_f32 v[96:97], v[190:191], s[10:11], v[96:97] op_sel_hi:[1,0,1]
	v_pk_fma_f32 v[94:95], v[188:189], s[10:11], v[94:95] op_sel_hi:[1,0,1]
	v_pk_fma_f32 v[92:93], v[186:187], s[10:11], v[92:93] op_sel_hi:[1,0,1]
	v_pk_fma_f32 v[90:91], v[184:185], s[10:11], v[90:91] op_sel_hi:[1,0,1]
	v_pk_fma_f32 v[112:113], v[206:207], s[10:11], v[112:113] op_sel_hi:[1,0,1]
	v_pk_fma_f32 v[110:111], v[204:205], s[10:11], v[110:111] op_sel_hi:[1,0,1]
	v_pk_fma_f32 v[100:101], v[202:203], s[10:11], v[100:101] op_sel_hi:[1,0,1]
	v_pk_fma_f32 v[98:99], v[200:201], s[10:11], v[98:99] op_sel_hi:[1,0,1]
	global_store_dwordx4 v[234:235], v[126:129], off
	global_store_dwordx4 v[234:235], v[122:125], off offset:16
	global_store_dwordx4 v[234:235], v[106:109], off offset:512
	global_store_dwordx4 v[234:235], v[102:105], off offset:528
	global_store_dwordx4 v[228:229], v[118:121], off
	global_store_dwordx4 v[228:229], v[114:117], off offset:16
	global_store_dwordx4 v[228:229], v[94:97], off offset:512
	global_store_dwordx4 v[228:229], v[90:93], off offset:528
	global_store_dwordx4 v[230:231], v[110:113], off
	global_store_dwordx4 v[230:231], v[98:101], off offset:16
	global_store_dwordx4 v[230:231], v[82:85], off offset:512
	v_pk_fma_f32 v[76:77], v[210:211], s[10:11], v[76:77] op_sel_hi:[1,0,1]
	v_pk_fma_f32 v[74:75], v[208:209], s[10:11], v[74:75] op_sel_hi:[1,0,1]
	v_lshl_add_u64 v[82:83], s[6:7], 0, v[232:233]
	global_store_dwordx4 v[230:231], v[74:77], off offset:528
	v_lshl_add_u64 v[82:83], v[82:83], 0, v[146:147]
	v_pk_fma_f32 v[72:73], v[226:227], s[10:11], v[72:73] op_sel_hi:[1,0,1]
	v_pk_fma_f32 v[76:77], v[218:219], s[10:11], v[88:89] op_sel_hi:[1,0,1]
	v_pk_fma_f32 v[74:75], v[216:217], s[10:11], v[86:87] op_sel_hi:[1,0,1]
	global_store_dwordx4 v[82:83], v[74:77], off
	v_pk_fma_f32 v[70:71], v[224:225], s[10:11], v[70:71] op_sel_hi:[1,0,1]
	v_pk_fma_f32 v[68:69], v[132:133], s[10:11], v[68:69] op_sel_hi:[1,0,1]
	v_pk_fma_f32 v[76:77], v[222:223], s[10:11], v[80:81] op_sel_hi:[1,0,1]
	v_pk_fma_f32 v[74:75], v[220:221], s[10:11], v[78:79] op_sel_hi:[1,0,1]
	v_pk_fma_f32 v[66:67], v[130:131], s[10:11], v[66:67] op_sel_hi:[1,0,1]
	v_lshl_add_u64 v[130:131], v[150:151], 0, s[12:13]
	v_lshl_add_u64 v[132:133], v[150:151], 0, s[14:15]
	global_store_dwordx4 v[82:83], v[74:77], off offset:16
	global_store_dwordx4 v[82:83], v[70:73], off offset:512
	global_store_dwordx4 v[82:83], v[66:69], off offset:528
	v_lshl_add_u64 v[78:79], v[148:149], 0, v[130:131]
	v_lshl_add_u64 v[94:95], v[148:149], 0, v[132:133]
	v_lshl_add_u64 v[158:159], v[150:151], 0, s[16:17]
	v_lshl_add_u64 v[150:151], v[150:151], 0, s[18:19]
	global_load_dwordx4 v[66:69], v[78:79], off offset:16
	global_load_dwordx4 v[70:73], v[78:79], off
	global_load_dwordx4 v[74:77], v[78:79], off offset:528
	s_nop 0
	global_load_dwordx4 v[78:81], v[78:79], off offset:512
	s_nop 0
	global_load_dwordx4 v[82:85], v[94:95], off offset:16
	global_load_dwordx4 v[86:89], v[94:95], off
	global_load_dwordx4 v[90:93], v[94:95], off offset:528
	s_nop 0
	global_load_dwordx4 v[94:97], v[94:95], off offset:512
	v_lshl_add_u64 v[110:111], v[148:149], 0, v[158:159]
	v_lshl_add_u64 v[126:127], v[148:149], 0, v[150:151]
	global_load_dwordx4 v[98:101], v[110:111], off offset:16
	global_load_dwordx4 v[102:105], v[110:111], off
	global_load_dwordx4 v[106:109], v[110:111], off offset:528
	s_nop 0
	global_load_dwordx4 v[110:113], v[110:111], off offset:512
	s_nop 0
	global_load_dwordx4 v[114:117], v[126:127], off
	global_load_dwordx4 v[118:121], v[126:127], off offset:16
	global_load_dwordx4 v[122:125], v[126:127], off offset:512
	s_nop 0
	global_load_dwordx4 v[126:129], v[126:127], off offset:528
	v_lshl_add_u64 v[130:131], s[6:7], 0, v[130:131]
	v_lshl_add_u64 v[132:133], s[6:7], 0, v[132:133]
	v_lshl_add_u64 v[130:131], v[130:131], 0, v[146:147]
	v_lshl_add_u64 v[132:133], v[132:133], 0, v[146:147]
	s_waitcnt vmcnt(14)
	s_waitcnt vmcnt(12)
	s_waitcnt vmcnt(10)
	s_waitcnt vmcnt(8)
	v_pk_fma_f32 v[64:65], v[72:73], s[10:11], v[64:65] op_sel_hi:[1,0,1]
	v_pk_fma_f32 v[62:63], v[70:71], s[10:11], v[62:63] op_sel_hi:[1,0,1]
	v_pk_fma_f32 v[36:37], v[96:97], s[10:11], v[36:37] op_sel_hi:[1,0,1]
	v_pk_fma_f32 v[34:35], v[94:95], s[10:11], v[34:35] op_sel_hi:[1,0,1]
	s_waitcnt vmcnt(6)
	s_waitcnt vmcnt(4)
	s_waitcnt vmcnt(3)
	s_waitcnt vmcnt(2)
	s_waitcnt vmcnt(1)
	s_waitcnt vmcnt(0)
	v_pk_fma_f32 v[60:61], v[68:69], s[10:11], v[60:61] op_sel_hi:[1,0,1]
	v_pk_fma_f32 v[58:59], v[66:67], s[10:11], v[58:59] op_sel_hi:[1,0,1]
	v_pk_fma_f32 v[48:49], v[80:81], s[10:11], v[48:49] op_sel_hi:[1,0,1]
	v_pk_fma_f32 v[46:47], v[78:79], s[10:11], v[46:47] op_sel_hi:[1,0,1]
	v_pk_fma_f32 v[44:45], v[76:77], s[10:11], v[44:45] op_sel_hi:[1,0,1]
	v_pk_fma_f32 v[42:43], v[74:75], s[10:11], v[42:43] op_sel_hi:[1,0,1]
	v_pk_fma_f32 v[56:57], v[88:89], s[10:11], v[56:57] op_sel_hi:[1,0,1]
	v_pk_fma_f32 v[54:55], v[86:87], s[10:11], v[54:55] op_sel_hi:[1,0,1]
	v_pk_fma_f32 v[52:53], v[84:85], s[10:11], v[52:53] op_sel_hi:[1,0,1]
	v_pk_fma_f32 v[50:51], v[82:83], s[10:11], v[50:51] op_sel_hi:[1,0,1]
	global_store_dwordx4 v[130:131], v[62:65], off
	global_store_dwordx4 v[130:131], v[58:61], off offset:16
	global_store_dwordx4 v[130:131], v[46:49], off offset:512
	global_store_dwordx4 v[130:131], v[42:45], off offset:528
	global_store_dwordx4 v[132:133], v[54:57], off
	global_store_dwordx4 v[132:133], v[50:53], off offset:16
	global_store_dwordx4 v[132:133], v[34:37], off offset:512
	v_pk_fma_f32 v[20:21], v[112:113], s[10:11], v[20:21] op_sel_hi:[1,0,1]
	v_pk_fma_f32 v[18:19], v[110:111], s[10:11], v[18:19] op_sel_hi:[1,0,1]
	v_lshl_add_u64 v[34:35], s[6:7], 0, v[158:159]
	v_lshl_add_u64 v[34:35], v[34:35], 0, v[146:147]
	v_pk_fma_f32 v[28:29], v[92:93], s[10:11], v[28:29] op_sel_hi:[1,0,1]
	v_pk_fma_f32 v[26:27], v[90:91], s[10:11], v[26:27] op_sel_hi:[1,0,1]
	global_store_dwordx4 v[34:35], v[18:21], off offset:512
	v_pk_fma_f32 v[12:13], v[108:109], s[10:11], v[12:13] op_sel_hi:[1,0,1]
	v_pk_fma_f32 v[10:11], v[106:107], s[10:11], v[10:11] op_sel_hi:[1,0,1]
	v_lshl_add_u64 v[18:19], s[6:7], 0, v[150:151]
	global_store_dwordx4 v[132:133], v[26:29], off offset:528
	global_store_dwordx4 v[34:35], v[10:13], off offset:528
	v_lshl_add_u64 v[18:19], v[18:19], 0, v[146:147]
	v_pk_fma_f32 v[28:29], v[104:105], s[10:11], v[40:41] op_sel_hi:[1,0,1]
	v_pk_fma_f32 v[26:27], v[102:103], s[10:11], v[38:39] op_sel_hi:[1,0,1]
	v_pk_fma_f32 v[12:13], v[116:117], s[10:11], v[24:25] op_sel_hi:[1,0,1]
	v_pk_fma_f32 v[10:11], v[114:115], s[10:11], v[22:23] op_sel_hi:[1,0,1]
	global_store_dwordx4 v[34:35], v[26:29], off
	global_store_dwordx4 v[18:19], v[10:13], off
	v_pk_fma_f32 v[8:9], v[124:125], s[10:11], v[8:9] op_sel_hi:[1,0,1]
	v_pk_fma_f32 v[28:29], v[100:101], s[10:11], v[32:33] op_sel_hi:[1,0,1]
	v_pk_fma_f32 v[26:27], v[98:99], s[10:11], v[30:31] op_sel_hi:[1,0,1]
	v_pk_fma_f32 v[12:13], v[120:121], s[10:11], v[16:17] op_sel_hi:[1,0,1]
	v_pk_fma_f32 v[10:11], v[118:119], s[10:11], v[14:15] op_sel_hi:[1,0,1]
	v_pk_fma_f32 v[6:7], v[122:123], s[10:11], v[6:7] op_sel_hi:[1,0,1]
	v_pk_fma_f32 v[4:5], v[128:129], s[10:11], v[4:5] op_sel_hi:[1,0,1]
	v_pk_fma_f32 v[2:3], v[126:127], s[10:11], v[2:3] op_sel_hi:[1,0,1]
	global_store_dwordx4 v[34:35], v[26:29], off offset:16
	global_store_dwordx4 v[18:19], v[10:13], off offset:16
	global_store_dwordx4 v[18:19], v[6:9], off offset:512
	global_store_dwordx4 v[18:19], v[2:5], off offset:528
	s_cbranch_vccnz .LBB0_812
	s_andn2_b64 vcc, exec, s[2:3]
	s_cbranch_vccnz .LBB0_811
	s_nop 0
	s_branch .LBB0_811

.LBB0_1591:
	s_add_u32 s33, s92, 0x13000000
	s_addc_u32 s40, s93, 0
	s_add_u32 s41, s92, 0x9000000
	s_addc_u32 s42, s93, 0
	s_add_i32 s0, s4, s0
	s_ashr_i32 s4, s0, 31
	s_lshr_b32 s4, s4, 25
	s_add_i32 s4, s0, s4
	s_ashr_i32 s5, s4, 7
	s_and_b32 s4, s4, 0xff80
	s_sub_i32 s4, s0, s4
	s_bfe_i32 s0, s4, 0x80000
	s_bfe_u32 s0, s0, 0x3000c
	s_add_i32 s6, s4, s0
	s_bfe_i32 s0, s6, 0x80000
	s_and_b32 s6, s6, 0xf8
	s_sub_i32 s4, s4, s6
	s_lshl_b32 s5, s5, 3
	s_sext_i32_i16 s0, s0
	s_sext_i32_i8 s4, s4
	s_lshr_b32 s1, s8, 8
	s_lshr_b32 s0, s0, 3
	s_add_i32 s28, s5, s4
	s_lshr_b32 s9, s8, 6
	s_ashr_i32 s29, s28, 31
	s_bfe_i64 s[6:7], s[0:1], 0x100000
	s_lshl_b32 s43, s9, 10
	s_lshl_b64 s[4:5], s[28:29], 21
	s_lshl_b64 s[6:7], s[6:7], 21
	v_lshlrev_b32_e32 v1, 4, v0
	s_add_u32 s34, s41, s6
	v_and_b32_e32 v2, 0x3f0, v1
	s_addc_u32 s35, s42, s7
	s_add_i32 s29, s43, 0
	v_or_b32_e32 v134, s43, v2
	s_add_i32 m0, s29, 0x10000
	v_add_u32_e32 v136, 0x2000, v134
	global_load_lds_dwordx4 v134, s[34:35]
	s_add_i32 m0, s29, 0x12000
	s_add_u32 s6, s34, 0x100000
	global_load_lds_dwordx4 v136, s[34:35]
	s_addc_u32 s7, s35, 0
	s_add_i32 m0, s29, 0x14000
	v_mov_b32_e32 v135, 0
	global_load_lds_dwordx4 v134, s[6:7]
	s_add_i32 m0, s29, 0x16000
	s_add_u32 s30, s33, s4
	s_addc_u32 s31, s40, s5
	s_add_i32 s44, s29, 0x2000
	global_load_lds_dwordx4 v136, s[6:7]
	s_mov_b32 m0, s29
	s_add_u32 s4, s30, 0x100000
	global_load_lds_dwordx4 v134, s[30:31]
	s_mov_b32 m0, s44
	s_addc_u32 s5, s31, 0
	s_add_i32 s45, s29, 0x4000
	global_load_lds_dwordx4 v136, s[30:31]
	s_mov_b32 m0, s45
	s_add_i32 s46, s29, 0x6000
	global_load_lds_dwordx4 v134, s[4:5]
	s_mov_b32 m0, s46
	s_cmp_eq_u32 s1, 1
	global_load_lds_dwordx4 v136, s[4:5]
	s_mov_b32 s47, 0
	s_cselect_b64 s[4:5], -1, 0
	s_cmp_lg_u32 s1, 1
	v_mov_b32_e32 v137, v135
	s_cbranch_scc1 .LBB0_1593
	s_nop 0
.LBB0_1593:
	s_add_u32 s6, s92, 0x53800000
	s_addc_u32 s7, s93, 0
	s_lshl_b32 s9, s9, 5
	s_and_b32 s14, s9, 0x60
	s_lshl_b32 s10, s1, 13
	s_lshl_b32 s9, s14, 7
	s_add_u32 s12, s34, 0x4000
	s_addc_u32 s13, s35, 0
	s_add_i32 m0, s29, 0x18000
	v_lshl_add_u64 v[4:5], s[12:13], 0, v[134:135]
	s_waitcnt vmcnt(2)
	s_barrier
	global_load_lds_dwordx4 v[4:5], off
	s_add_i32 m0, s29, 0x1a000
	v_lshl_add_u64 v[4:5], s[12:13], 0, v[136:137]
	s_add_u32 s12, s30, 0x4000
	s_addc_u32 s13, s31, 0
	s_add_i32 s48, s29, 0x8000
	global_load_lds_dwordx4 v[4:5], off
	v_lshl_add_u64 v[4:5], s[12:13], 0, v[134:135]
	s_mov_b32 m0, s48
	s_add_i32 s49, s29, 0xa000
	global_load_lds_dwordx4 v[4:5], off
	v_lshl_add_u64 v[4:5], s[12:13], 0, v[136:137]
	s_add_u32 s12, s34, 0x104000
	s_mov_b32 m0, s49
	s_addc_u32 s13, s35, 0
	global_load_lds_dwordx4 v[4:5], off
	s_add_i32 m0, s29, 0x1c000
	v_lshl_add_u64 v[4:5], s[12:13], 0, v[134:135]
	global_load_lds_dwordx4 v[4:5], off
	v_lshl_add_u64 v[4:5], s[12:13], 0, v[136:137]
	s_add_i32 m0, s29, 0x1e000
	v_lshrrev_b32_e32 v1, 1, v0
	global_load_lds_dwordx4 v[4:5], off
	v_and_b32_e32 v4, 24, v1
	s_sext_i32_i8 s53, s0
	v_and_b32_e32 v3, 15, v0
	v_lshlrev_b32_e32 v5, 1, v4
	v_lshlrev_b32_e32 v7, 6, v0
	s_movk_i32 s0, 0x3c0
	v_lshl_or_b32 v1, s1, 6, v3
	v_lshl_or_b32 v3, v3, 6, v5
	v_and_b32_e32 v6, 32, v179
	v_and_or_b32 v5, v7, s0, v5
	s_waitcnt vmcnt(6)
	s_cmpk_lt_u32 s8, 0x100
	v_bitop3_b32 v3, v3, s10, v6 bitop3:0xde
	v_bitop3_b32 v152, s9, v5, v6 bitop3:0xf6
	s_cselect_b64 s[8:9], -1, 0
	v_readlane_b32 s0, v249, 34
	v_add_u32_e32 v138, s43, v2
	s_add_i32 s51, 0, 0x10000
	s_add_i32 s52, 0, 0x14000
	s_ashr_i32 s50, s0, 31
	v_or_b32_e32 v153, s14, v4
	v_mov_b32_e32 v139, v135
	v_add_u32_e32 v140, 0x2000, v138
	v_mov_b32_e32 v141, v135
	v_mov_b64_e32 v[142:143], 0x200
	v_mov_b64_e32 v[144:145], 0x1ff
	v_add_u32_e32 v154, s51, v152
	v_add_u32_e32 v155, s52, v152
	v_add_u32_e32 v156, 0, v3
	s_mov_b32 s10, 0x3fb504f3
	s_mov_b64 s[12:13], 0x200000
	s_mov_b64 s[14:15], 0x240000
	s_mov_b64 s[16:17], 0x280000
	s_mov_b64 s[18:19], 0x2c0000
	s_barrier
	v_readlane_b32 s1, v249, 35
	s_mov_b32 s32, 1
	s_branch .LBB0_1596

.Lb16_rd_o1:
	ds_read_b128 v[184:187], v156
	ds_read_b128 v[188:191], v156 offset:1024
	ds_read_b128 v[192:195], v156 offset:2048
	ds_read_b128 v[196:199], v156 offset:3072
	ds_read_b128 v[200:203], v156 offset:4096
	ds_read_b128 v[204:207], v156 offset:5120
	ds_read_b128 v[208:211], v156 offset:6144
	ds_read_b128 v[212:215], v156 offset:7168
	ds_read_b128 v[130:133], v154
	ds_read_b128 v[146:149], v154 offset:1024
	ds_read_b128 v[158:161], v154 offset:2048
	ds_read_b128 v[162:165], v154 offset:3072
	ds_read_b128 v[166:169], v154 offset:16384
	ds_read_b128 v[170:173], v154 offset:17408
	ds_read_b128 v[174:177], v154 offset:18432
	ds_read_b128 v[180:183], v154 offset:19456
	s_waitcnt lgkmcnt(0)
	s_barrier
.Lb16_top_o1:
	s_add_u32 s34, s30, 0xfff04000
	s_addc_u32 s35, s31, -1
	s_cmp_eq_u32 s58, 60
	s_cselect_b32 s38, s54, s34
	s_cselect_b32 s39, s23, s35
	s_cselect_b32 s36, s55, s56
	s_cselect_b32 s37, s21, s57
	s_add_u32 s34, s36, 0x100000
	s_addc_u32 s35, s37, 0
	s_add_i32 m0, s29, 0x0
	v_mfma_f32_16x16x32_bf16 v[126:129], v[130:133], v[184:187], v[126:129]
	global_load_lds_dwordx4 v134, s[38:39]
	v_mfma_f32_16x16x32_bf16 v[126:129], v[146:149], v[188:191], v[126:129]
	v_mfma_f32_16x16x32_bf16 v[122:125], v[158:161], v[184:187], v[122:125]
	ds_read_b128 v[224:227], v156 offset:22528
	v_mfma_f32_16x16x32_bf16 v[122:125], v[162:165], v[188:191], v[122:125]
	v_mfma_f32_16x16x32_bf16 v[106:109], v[166:169], v[184:187], v[106:109]
	ds_read_b128 v[228:231], v156 offset:23552
	v_mfma_f32_16x16x32_bf16 v[106:109], v[170:173], v[188:191], v[106:109]
	s_add_i32 m0, s29, 0x2000
	v_mfma_f32_16x16x32_bf16 v[102:105], v[174:177], v[184:187], v[102:105]
	global_load_lds_dwordx4 v136, s[38:39]
	v_mfma_f32_16x16x32_bf16 v[102:105], v[180:183], v[188:191], v[102:105]
	ds_read_b128 v[184:187], v156 offset:16384
	ds_read_b128 v[188:191], v156 offset:17408
	s_add_i32 m0, s29, 0x10000
	v_mfma_f32_16x16x32_bf16 v[118:121], v[130:133], v[192:195], v[118:121]
	global_load_lds_dwordx4 v134, s[36:37]
	v_mfma_f32_16x16x32_bf16 v[118:121], v[146:149], v[196:199], v[118:121]
	s_add_i32 m0, s29, 0x12000
	v_mfma_f32_16x16x32_bf16 v[114:117], v[158:161], v[192:195], v[114:117]
	global_load_lds_dwordx4 v136, s[36:37]
	v_mfma_f32_16x16x32_bf16 v[114:117], v[162:165], v[196:199], v[114:117]
	s_add_i32 m0, s29, 0x14000
	v_mfma_f32_16x16x32_bf16 v[94:97], v[166:169], v[192:195], v[94:97]
	global_load_lds_dwordx4 v134, s[34:35]
	v_mfma_f32_16x16x32_bf16 v[94:97], v[170:173], v[196:199], v[94:97]
	s_add_i32 m0, s29, 0x16000
	v_mfma_f32_16x16x32_bf16 v[90:93], v[174:177], v[192:195], v[90:93]
	global_load_lds_dwordx4 v136, s[34:35]
	v_mfma_f32_16x16x32_bf16 v[90:93], v[180:183], v[196:199], v[90:93]
	ds_read_b128 v[192:195], v156 offset:18432
	ds_read_b128 v[196:199], v156 offset:19456
	v_mfma_f32_16x16x32_bf16 v[110:113], v[130:133], v[200:203], v[110:113]
	v_mfma_f32_16x16x32_bf16 v[110:113], v[146:149], v[204:207], v[110:113]
	v_mfma_f32_16x16x32_bf16 v[98:101], v[158:161], v[200:203], v[98:101]
	v_mfma_f32_16x16x32_bf16 v[98:101], v[162:165], v[204:207], v[98:101]
	v_mfma_f32_16x16x32_bf16 v[82:85], v[166:169], v[200:203], v[82:85]
	v_mfma_f32_16x16x32_bf16 v[82:85], v[170:173], v[204:207], v[82:85]
	v_mfma_f32_16x16x32_bf16 v[74:77], v[174:177], v[200:203], v[74:77]
	v_mfma_f32_16x16x32_bf16 v[74:77], v[180:183], v[204:207], v[74:77]
	ds_read_b128 v[200:203], v156 offset:20480
	ds_read_b128 v[204:207], v156 offset:21504
	v_mfma_f32_16x16x32_bf16 v[86:89], v[130:133], v[208:211], v[86:89]
	v_mfma_f32_16x16x32_bf16 v[86:89], v[146:149], v[212:215], v[86:89]
	v_mfma_f32_16x16x32_bf16 v[78:81], v[158:161], v[208:211], v[78:81]
	v_mfma_f32_16x16x32_bf16 v[78:81], v[162:165], v[212:215], v[78:81]
	v_mfma_f32_16x16x32_bf16 v[70:73], v[166:169], v[208:211], v[70:73]
	v_mfma_f32_16x16x32_bf16 v[70:73], v[170:173], v[212:215], v[70:73]
	v_mfma_f32_16x16x32_bf16 v[66:69], v[174:177], v[208:211], v[66:69]
	v_mfma_f32_16x16x32_bf16 v[66:69], v[180:183], v[212:215], v[66:69]
	s_waitcnt vmcnt(8)
	s_waitcnt lgkmcnt(0)
	s_barrier
	s_add_u32 s34, s38, 0x100000
	s_addc_u32 s35, s39, 0
	s_add_i32 m0, s29, 0x4000
	v_mfma_f32_16x16x32_bf16 v[62:65], v[130:133], v[184:187], v[62:65]
	global_load_lds_dwordx4 v134, s[34:35]
	v_mfma_f32_16x16x32_bf16 v[62:65], v[146:149], v[188:191], v[62:65]
	v_mfma_f32_16x16x32_bf16 v[58:61], v[158:161], v[184:187], v[58:61]
	ds_read_b128 v[208:211], v156 offset:38912
	v_mfma_f32_16x16x32_bf16 v[58:61], v[162:165], v[188:191], v[58:61]
	v_mfma_f32_16x16x32_bf16 v[46:49], v[166:169], v[184:187], v[46:49]
	ds_read_b128 v[212:215], v156 offset:39936
	v_mfma_f32_16x16x32_bf16 v[46:49], v[170:173], v[188:191], v[46:49]
	s_add_i32 m0, s29, 0x6000
	v_mfma_f32_16x16x32_bf16 v[42:45], v[174:177], v[184:187], v[42:45]
	global_load_lds_dwordx4 v136, s[34:35]
	v_mfma_f32_16x16x32_bf16 v[42:45], v[180:183], v[188:191], v[42:45]
	ds_read_b128 v[184:187], v156 offset:32768
	ds_read_b128 v[188:191], v156 offset:33792
	v_mfma_f32_16x16x32_bf16 v[54:57], v[130:133], v[192:195], v[54:57]
	ds_read_b128 v[232:235], v154 offset:49152
	v_mfma_f32_16x16x32_bf16 v[54:57], v[146:149], v[196:199], v[54:57]
	v_mfma_f32_16x16x32_bf16 v[50:53], v[158:161], v[192:195], v[50:53]
	ds_read_b128 v[236:239], v154 offset:50176
	v_mfma_f32_16x16x32_bf16 v[50:53], v[162:165], v[196:199], v[50:53]
	v_mfma_f32_16x16x32_bf16 v[34:37], v[166:169], v[192:195], v[34:37]
	ds_read_b128 v[240:243], v154 offset:51200
	v_mfma_f32_16x16x32_bf16 v[34:37], v[170:173], v[196:199], v[34:37]
	v_mfma_f32_16x16x32_bf16 v[26:29], v[174:177], v[192:195], v[26:29]
	ds_read_b128 v[244:247], v154 offset:52224
	v_mfma_f32_16x16x32_bf16 v[26:29], v[180:183], v[196:199], v[26:29]
	ds_read_b128 v[192:195], v156 offset:34816
	ds_read_b128 v[196:199], v156 offset:35840
	v_mfma_f32_16x16x32_bf16 v[38:41], v[130:133], v[200:203], v[38:41]
	v_mfma_f32_16x16x32_bf16 v[38:41], v[146:149], v[204:207], v[38:41]
	v_mfma_f32_16x16x32_bf16 v[30:33], v[158:161], v[200:203], v[30:33]
	v_mfma_f32_16x16x32_bf16 v[30:33], v[162:165], v[204:207], v[30:33]
	v_mfma_f32_16x16x32_bf16 v[18:21], v[166:169], v[200:203], v[18:21]
	v_mfma_f32_16x16x32_bf16 v[18:21], v[170:173], v[204:207], v[18:21]
	v_mfma_f32_16x16x32_bf16 v[10:13], v[174:177], v[200:203], v[10:13]
	v_mfma_f32_16x16x32_bf16 v[10:13], v[180:183], v[204:207], v[10:13]
	ds_read_b128 v[200:203], v156 offset:36864
	ds_read_b128 v[204:207], v156 offset:37888
	v_mfma_f32_16x16x32_bf16 v[22:25], v[130:133], v[224:227], v[22:25]
	v_mfma_f32_16x16x32_bf16 v[22:25], v[146:149], v[228:231], v[22:25]
	ds_read_b128 v[130:133], v154 offset:32768
	ds_read_b128 v[146:149], v154 offset:33792
	v_mfma_f32_16x16x32_bf16 v[14:17], v[158:161], v[224:227], v[14:17]
	v_mfma_f32_16x16x32_bf16 v[14:17], v[162:165], v[228:231], v[14:17]
	ds_read_b128 v[158:161], v154 offset:34816
	ds_read_b128 v[162:165], v154 offset:35840
	v_mfma_f32_16x16x32_bf16 v[6:9], v[166:169], v[224:227], v[6:9]
	v_mfma_f32_16x16x32_bf16 v[6:9], v[170:173], v[228:231], v[6:9]
	v_mfma_f32_16x16x32_bf16 v[2:5], v[174:177], v[224:227], v[2:5]
	v_mfma_f32_16x16x32_bf16 v[2:5], v[180:183], v[228:231], v[2:5]
	s_waitcnt vmcnt(8)
	s_waitcnt lgkmcnt(0)
	s_barrier
	s_add_u32 s38, s38, 0x4000
	s_addc_u32 s39, s39, 0
	s_add_u32 s36, s36, 0x4000
	s_addc_u32 s37, s37, 0
	s_add_u32 s34, s36, 0x100000
	s_addc_u32 s35, s37, 0
	s_add_i32 m0, s29, 0x8000
	v_mfma_f32_16x16x32_bf16 v[126:129], v[130:133], v[184:187], v[126:129]
	global_load_lds_dwordx4 v134, s[38:39]
	v_mfma_f32_16x16x32_bf16 v[126:129], v[146:149], v[188:191], v[126:129]
	v_mfma_f32_16x16x32_bf16 v[122:125], v[158:161], v[184:187], v[122:125]
	ds_read_b128 v[224:227], v156 offset:55296
	v_mfma_f32_16x16x32_bf16 v[122:125], v[162:165], v[188:191], v[122:125]
	v_mfma_f32_16x16x32_bf16 v[106:109], v[232:235], v[184:187], v[106:109]
	ds_read_b128 v[228:231], v156 offset:56320
	v_mfma_f32_16x16x32_bf16 v[106:109], v[236:239], v[188:191], v[106:109]
	s_add_i32 m0, s29, 0xa000
	v_mfma_f32_16x16x32_bf16 v[102:105], v[240:243], v[184:187], v[102:105]
	global_load_lds_dwordx4 v136, s[38:39]
	v_mfma_f32_16x16x32_bf16 v[102:105], v[244:247], v[188:191], v[102:105]
	ds_read_b128 v[184:187], v156 offset:49152
	ds_read_b128 v[188:191], v156 offset:50176
	s_add_i32 m0, s29, 0x18000
	v_mfma_f32_16x16x32_bf16 v[118:121], v[130:133], v[192:195], v[118:121]
	global_load_lds_dwordx4 v134, s[36:37]
	v_mfma_f32_16x16x32_bf16 v[118:121], v[146:149], v[196:199], v[118:121]
	s_add_i32 m0, s29, 0x1a000
	v_mfma_f32_16x16x32_bf16 v[114:117], v[158:161], v[192:195], v[114:117]
	global_load_lds_dwordx4 v136, s[36:37]
	v_mfma_f32_16x16x32_bf16 v[114:117], v[162:165], v[196:199], v[114:117]
	s_add_i32 m0, s29, 0x1c000
	v_mfma_f32_16x16x32_bf16 v[94:97], v[232:235], v[192:195], v[94:97]
	global_load_lds_dwordx4 v134, s[34:35]
	v_mfma_f32_16x16x32_bf16 v[94:97], v[236:239], v[196:199], v[94:97]
	s_add_i32 m0, s29, 0x1e000
	v_mfma_f32_16x16x32_bf16 v[90:93], v[240:243], v[192:195], v[90:93]
	global_load_lds_dwordx4 v136, s[34:35]
	v_mfma_f32_16x16x32_bf16 v[90:93], v[244:247], v[196:199], v[90:93]
	ds_read_b128 v[192:195], v156 offset:51200
	ds_read_b128 v[196:199], v156 offset:52224
	v_mfma_f32_16x16x32_bf16 v[110:113], v[130:133], v[200:203], v[110:113]
	v_mfma_f32_16x16x32_bf16 v[110:113], v[146:149], v[204:207], v[110:113]
	v_mfma_f32_16x16x32_bf16 v[98:101], v[158:161], v[200:203], v[98:101]
	v_mfma_f32_16x16x32_bf16 v[98:101], v[162:165], v[204:207], v[98:101]
	v_mfma_f32_16x16x32_bf16 v[82:85], v[232:235], v[200:203], v[82:85]
	v_mfma_f32_16x16x32_bf16 v[82:85], v[236:239], v[204:207], v[82:85]
	v_mfma_f32_16x16x32_bf16 v[74:77], v[240:243], v[200:203], v[74:77]
	v_mfma_f32_16x16x32_bf16 v[74:77], v[244:247], v[204:207], v[74:77]
	ds_read_b128 v[200:203], v156 offset:53248
	ds_read_b128 v[204:207], v156 offset:54272
	v_mfma_f32_16x16x32_bf16 v[86:89], v[130:133], v[208:211], v[86:89]
	v_mfma_f32_16x16x32_bf16 v[86:89], v[146:149], v[212:215], v[86:89]
	v_mfma_f32_16x16x32_bf16 v[78:81], v[158:161], v[208:211], v[78:81]
	v_mfma_f32_16x16x32_bf16 v[78:81], v[162:165], v[212:215], v[78:81]
	v_mfma_f32_16x16x32_bf16 v[70:73], v[232:235], v[208:211], v[70:73]
	v_mfma_f32_16x16x32_bf16 v[70:73], v[236:239], v[212:215], v[70:73]
	v_mfma_f32_16x16x32_bf16 v[66:69], v[240:243], v[208:211], v[66:69]
	v_mfma_f32_16x16x32_bf16 v[66:69], v[244:247], v[212:215], v[66:69]
	s_waitcnt vmcnt(8)
	s_waitcnt lgkmcnt(0)
	s_barrier
	s_add_u32 s34, s38, 0x100000
	s_addc_u32 s35, s39, 0
	s_add_i32 m0, s29, 0xc000
	v_mfma_f32_16x16x32_bf16 v[62:65], v[130:133], v[184:187], v[62:65]
	global_load_lds_dwordx4 v134, s[34:35]
	v_mfma_f32_16x16x32_bf16 v[62:65], v[146:149], v[188:191], v[62:65]
	v_mfma_f32_16x16x32_bf16 v[58:61], v[158:161], v[184:187], v[58:61]
	ds_read_b128 v[208:211], v156 offset:6144
	v_mfma_f32_16x16x32_bf16 v[58:61], v[162:165], v[188:191], v[58:61]
	v_mfma_f32_16x16x32_bf16 v[46:49], v[232:235], v[184:187], v[46:49]
	ds_read_b128 v[212:215], v156 offset:7168
	v_mfma_f32_16x16x32_bf16 v[46:49], v[236:239], v[188:191], v[46:49]
	s_add_i32 m0, s29, 0xe000
	v_mfma_f32_16x16x32_bf16 v[42:45], v[240:243], v[184:187], v[42:45]
	global_load_lds_dwordx4 v136, s[34:35]
	v_mfma_f32_16x16x32_bf16 v[42:45], v[244:247], v[188:191], v[42:45]
	ds_read_b128 v[184:187], v156
	ds_read_b128 v[188:191], v156 offset:1024
	v_mfma_f32_16x16x32_bf16 v[54:57], v[130:133], v[192:195], v[54:57]
	ds_read_b128 v[166:169], v154 offset:16384
	v_mfma_f32_16x16x32_bf16 v[54:57], v[146:149], v[196:199], v[54:57]
	v_mfma_f32_16x16x32_bf16 v[50:53], v[158:161], v[192:195], v[50:53]
	ds_read_b128 v[170:173], v154 offset:17408
	v_mfma_f32_16x16x32_bf16 v[50:53], v[162:165], v[196:199], v[50:53]
	v_mfma_f32_16x16x32_bf16 v[34:37], v[232:235], v[192:195], v[34:37]
	ds_read_b128 v[174:177], v154 offset:18432
	v_mfma_f32_16x16x32_bf16 v[34:37], v[236:239], v[196:199], v[34:37]
	v_mfma_f32_16x16x32_bf16 v[26:29], v[240:243], v[192:195], v[26:29]
	ds_read_b128 v[180:183], v154 offset:19456
	v_mfma_f32_16x16x32_bf16 v[26:29], v[244:247], v[196:199], v[26:29]
	ds_read_b128 v[192:195], v156 offset:2048
	ds_read_b128 v[196:199], v156 offset:3072
	v_mfma_f32_16x16x32_bf16 v[38:41], v[130:133], v[200:203], v[38:41]
	v_mfma_f32_16x16x32_bf16 v[38:41], v[146:149], v[204:207], v[38:41]
	v_mfma_f32_16x16x32_bf16 v[30:33], v[158:161], v[200:203], v[30:33]
	v_mfma_f32_16x16x32_bf16 v[30:33], v[162:165], v[204:207], v[30:33]
	v_mfma_f32_16x16x32_bf16 v[18:21], v[232:235], v[200:203], v[18:21]
	v_mfma_f32_16x16x32_bf16 v[18:21], v[236:239], v[204:207], v[18:21]
	v_mfma_f32_16x16x32_bf16 v[10:13], v[240:243], v[200:203], v[10:13]
	v_mfma_f32_16x16x32_bf16 v[10:13], v[244:247], v[204:207], v[10:13]
	ds_read_b128 v[200:203], v156 offset:4096
	ds_read_b128 v[204:207], v156 offset:5120
	v_mfma_f32_16x16x32_bf16 v[22:25], v[130:133], v[224:227], v[22:25]
	v_mfma_f32_16x16x32_bf16 v[22:25], v[146:149], v[228:231], v[22:25]
	ds_read_b128 v[130:133], v154
	ds_read_b128 v[146:149], v154 offset:1024
	v_mfma_f32_16x16x32_bf16 v[14:17], v[158:161], v[224:227], v[14:17]
	v_mfma_f32_16x16x32_bf16 v[14:17], v[162:165], v[228:231], v[14:17]
	ds_read_b128 v[158:161], v154 offset:2048
	ds_read_b128 v[162:165], v154 offset:3072
	v_mfma_f32_16x16x32_bf16 v[6:9], v[232:235], v[224:227], v[6:9]
	v_mfma_f32_16x16x32_bf16 v[6:9], v[236:239], v[228:231], v[6:9]
	v_mfma_f32_16x16x32_bf16 v[2:5], v[240:243], v[224:227], v[2:5]
	v_mfma_f32_16x16x32_bf16 v[2:5], v[244:247], v[228:231], v[2:5]
	s_waitcnt vmcnt(8)
	s_waitcnt lgkmcnt(0)
	s_barrier
	s_add_i32 s58, s58, 2
	s_add_u32 s30, s30, 0x8000
	s_addc_u32 s31, s31, 0
	s_add_u32 s56, s56, 0x8000
	s_addc_u32 s57, s57, 0
	s_cmp_gt_u32 s58, 61
	s_cbranch_scc0 .Lb16_top_o1
	s_nop 7
	s_and_b64 vcc, exec, s[8:9]
	s_cbranch_vccz .LBB0_1606
	s_nop 0
.LBB0_1606:
	v_lshl_or_b32 v132, s53, 8, v153
	v_lshl_add_u32 v130, s28, 8, v1
	v_ashrrev_i32_e32 v133, 31, v132
	v_readlane_b32 s56, v249, 16
	v_lshlrev_b64 v[146:147], 2, v[132:133]
	v_readlane_b32 s70, v249, 30
	v_readlane_b32 s71, v249, 31
	v_ashrrev_i32_e32 v131, 31, v130
	v_lshlrev_b64 v[150:151], 14, v[130:131]
	v_lshl_add_u64 v[148:149], s[70:71], 0, v[146:147]
	v_lshl_add_u64 v[132:133], v[148:149], 0, v[150:151]
	global_load_dwordx4 v[158:161], v[132:133], off offset:16
	global_load_dwordx4 v[162:165], v[132:133], off
	global_load_dwordx4 v[166:169], v[132:133], off offset:528
	global_load_dwordx4 v[170:173], v[132:133], off offset:512
	v_or_b32_e32 v132, 16, v130
	v_ashrrev_i32_e32 v133, 31, v132
	v_lshlrev_b64 v[220:221], 14, v[132:133]
	v_lshl_add_u64 v[132:133], v[148:149], 0, v[220:221]
	global_load_dwordx4 v[174:177], v[132:133], off offset:16
	global_load_dwordx4 v[180:183], v[132:133], off
	global_load_dwordx4 v[184:187], v[132:133], off offset:528
	global_load_dwordx4 v[188:191], v[132:133], off offset:512
	v_or_b32_e32 v132, 32, v130
	v_ashrrev_i32_e32 v133, 31, v132
	v_or_b32_e32 v130, 48, v130
	v_lshlrev_b64 v[222:223], 14, v[132:133]
	v_ashrrev_i32_e32 v131, 31, v130
	v_lshl_add_u64 v[132:133], v[148:149], 0, v[222:223]
	v_lshlrev_b64 v[224:225], 14, v[130:131]
	global_load_dwordx4 v[192:195], v[132:133], off offset:16
	global_load_dwordx4 v[196:199], v[132:133], off
	global_load_dwordx4 v[200:203], v[132:133], off offset:528
	global_load_dwordx4 v[204:207], v[132:133], off offset:512
	v_lshl_add_u64 v[130:131], v[148:149], 0, v[224:225]
	global_load_dwordx4 v[208:211], v[130:131], off
	global_load_dwordx4 v[212:215], v[130:131], off offset:16
	global_load_dwordx4 v[216:219], v[130:131], off offset:512
	s_nop 0
	global_load_dwordx4 v[130:133], v[130:131], off offset:528
	v_lshl_add_u64 v[226:227], s[6:7], 0, v[150:151]
	v_lshl_add_u64 v[222:223], s[6:7], 0, v[222:223]
	v_lshl_add_u64 v[226:227], v[226:227], 0, v[146:147]
	v_lshl_add_u64 v[220:221], s[6:7], 0, v[220:221]
	v_lshl_add_u64 v[222:223], v[222:223], 0, v[146:147]
	v_lshl_add_u64 v[220:221], v[220:221], 0, v[146:147]
	s_andn2_b64 vcc, exec, s[0:1]
	s_mov_b64 s[0:1], -1
	v_readlane_b32 s57, v249, 17
	v_readlane_b32 s58, v249, 18
	v_readlane_b32 s59, v249, 19
	v_readlane_b32 s60, v249, 20
	v_readlane_b32 s61, v249, 21
	v_readlane_b32 s62, v249, 22
	v_readlane_b32 s63, v249, 23
	v_readlane_b32 s64, v249, 24
	v_readlane_b32 s65, v249, 25
	v_readlane_b32 s66, v249, 26
	v_readlane_b32 s67, v249, 27
	v_readlane_b32 s68, v249, 28
	v_readlane_b32 s69, v249, 29
	s_waitcnt vmcnt(0)
	s_nop 0
	v_pk_fma_f32 v[128:129], v[164:165], s[10:11], v[128:129] op_sel_hi:[1,0,1]
	v_pk_fma_f32 v[126:127], v[162:163], s[10:11], v[126:127] op_sel_hi:[1,0,1]
	v_pk_fma_f32 v[84:85], v[206:207], s[10:11], v[84:85] op_sel_hi:[1,0,1]
	v_pk_fma_f32 v[82:83], v[204:205], s[10:11], v[82:83] op_sel_hi:[1,0,1]
	v_pk_fma_f32 v[124:125], v[160:161], s[10:11], v[124:125] op_sel_hi:[1,0,1]
	v_pk_fma_f32 v[122:123], v[158:159], s[10:11], v[122:123] op_sel_hi:[1,0,1]
	v_pk_fma_f32 v[108:109], v[172:173], s[10:11], v[108:109] op_sel_hi:[1,0,1]
	v_pk_fma_f32 v[106:107], v[170:171], s[10:11], v[106:107] op_sel_hi:[1,0,1]
	v_pk_fma_f32 v[104:105], v[168:169], s[10:11], v[104:105] op_sel_hi:[1,0,1]
	v_pk_fma_f32 v[102:103], v[166:167], s[10:11], v[102:103] op_sel_hi:[1,0,1]
	v_pk_fma_f32 v[120:121], v[182:183], s[10:11], v[120:121] op_sel_hi:[1,0,1]
	v_pk_fma_f32 v[118:119], v[180:181], s[10:11], v[118:119] op_sel_hi:[1,0,1]
	v_pk_fma_f32 v[116:117], v[176:177], s[10:11], v[116:117] op_sel_hi:[1,0,1]
	v_pk_fma_f32 v[114:115], v[174:175], s[10:11], v[114:115] op_sel_hi:[1,0,1]
	v_pk_fma_f32 v[96:97], v[190:191], s[10:11], v[96:97] op_sel_hi:[1,0,1]
	v_pk_fma_f32 v[94:95], v[188:189], s[10:11], v[94:95] op_sel_hi:[1,0,1]
	v_pk_fma_f32 v[92:93], v[186:187], s[10:11], v[92:93] op_sel_hi:[1,0,1]
	v_pk_fma_f32 v[90:91], v[184:185], s[10:11], v[90:91] op_sel_hi:[1,0,1]
	v_pk_fma_f32 v[112:113], v[198:199], s[10:11], v[112:113] op_sel_hi:[1,0,1]
	v_pk_fma_f32 v[110:111], v[196:197], s[10:11], v[110:111] op_sel_hi:[1,0,1]
	v_pk_fma_f32 v[100:101], v[194:195], s[10:11], v[100:101] op_sel_hi:[1,0,1]
	v_pk_fma_f32 v[98:99], v[192:193], s[10:11], v[98:99] op_sel_hi:[1,0,1]
	global_store_dwordx4 v[226:227], v[126:129], off
	global_store_dwordx4 v[226:227], v[122:125], off offset:16
	global_store_dwordx4 v[226:227], v[106:109], off offset:512
	global_store_dwordx4 v[226:227], v[102:105], off offset:528
	global_store_dwordx4 v[220:221], v[118:121], off
	global_store_dwordx4 v[220:221], v[114:117], off offset:16
	global_store_dwordx4 v[220:221], v[94:97], off offset:512
	global_store_dwordx4 v[220:221], v[90:93], off offset:528
	global_store_dwordx4 v[222:223], v[110:113], off
	global_store_dwordx4 v[222:223], v[98:101], off offset:16
	global_store_dwordx4 v[222:223], v[82:85], off offset:512
	v_pk_fma_f32 v[76:77], v[202:203], s[10:11], v[76:77] op_sel_hi:[1,0,1]
	v_pk_fma_f32 v[74:75], v[200:201], s[10:11], v[74:75] op_sel_hi:[1,0,1]
	v_lshl_add_u64 v[82:83], s[6:7], 0, v[224:225]
	global_store_dwordx4 v[222:223], v[74:77], off offset:528
	v_lshl_add_u64 v[82:83], v[82:83], 0, v[146:147]
	v_pk_fma_f32 v[72:73], v[218:219], s[10:11], v[72:73] op_sel_hi:[1,0,1]
	v_pk_fma_f32 v[76:77], v[210:211], s[10:11], v[88:89] op_sel_hi:[1,0,1]
	v_pk_fma_f32 v[74:75], v[208:209], s[10:11], v[86:87] op_sel_hi:[1,0,1]
	global_store_dwordx4 v[82:83], v[74:77], off
	v_pk_fma_f32 v[70:71], v[216:217], s[10:11], v[70:71] op_sel_hi:[1,0,1]
	v_pk_fma_f32 v[68:69], v[132:133], s[10:11], v[68:69] op_sel_hi:[1,0,1]
	v_pk_fma_f32 v[76:77], v[214:215], s[10:11], v[80:81] op_sel_hi:[1,0,1]
	v_pk_fma_f32 v[74:75], v[212:213], s[10:11], v[78:79] op_sel_hi:[1,0,1]
	v_pk_fma_f32 v[66:67], v[130:131], s[10:11], v[66:67] op_sel_hi:[1,0,1]
	v_lshl_add_u64 v[130:131], v[150:151], 0, s[12:13]
	v_lshl_add_u64 v[132:133], v[150:151], 0, s[14:15]
	global_store_dwordx4 v[82:83], v[74:77], off offset:16
	global_store_dwordx4 v[82:83], v[70:73], off offset:512
	global_store_dwordx4 v[82:83], v[66:69], off offset:528
	v_lshl_add_u64 v[78:79], v[148:149], 0, v[130:131]
	v_lshl_add_u64 v[94:95], v[148:149], 0, v[132:133]
	v_lshl_add_u64 v[158:159], v[150:151], 0, s[16:17]
	v_lshl_add_u64 v[150:151], v[150:151], 0, s[18:19]
	global_load_dwordx4 v[66:69], v[78:79], off offset:16
	global_load_dwordx4 v[70:73], v[78:79], off
	global_load_dwordx4 v[74:77], v[78:79], off offset:528
	s_nop 0
	global_load_dwordx4 v[78:81], v[78:79], off offset:512
	s_nop 0
	global_load_dwordx4 v[82:85], v[94:95], off offset:16
	global_load_dwordx4 v[86:89], v[94:95], off
	global_load_dwordx4 v[90:93], v[94:95], off offset:528
	s_nop 0
	global_load_dwordx4 v[94:97], v[94:95], off offset:512
	v_lshl_add_u64 v[110:111], v[148:149], 0, v[158:159]
	v_lshl_add_u64 v[126:127], v[148:149], 0, v[150:151]
	global_load_dwordx4 v[98:101], v[110:111], off offset:16
	global_load_dwordx4 v[102:105], v[110:111], off
	global_load_dwordx4 v[106:109], v[110:111], off offset:528
	s_nop 0
	global_load_dwordx4 v[110:113], v[110:111], off offset:512
	s_nop 0
	global_load_dwordx4 v[114:117], v[126:127], off
	global_load_dwordx4 v[118:121], v[126:127], off offset:16
	global_load_dwordx4 v[122:125], v[126:127], off offset:512
	s_nop 0
	global_load_dwordx4 v[126:129], v[126:127], off offset:528
	v_lshl_add_u64 v[130:131], s[6:7], 0, v[130:131]
	v_lshl_add_u64 v[132:133], s[6:7], 0, v[132:133]
	v_lshl_add_u64 v[130:131], v[130:131], 0, v[146:147]
	v_lshl_add_u64 v[132:133], v[132:133], 0, v[146:147]
	s_waitcnt vmcnt(14)
	s_waitcnt vmcnt(12)
	s_waitcnt vmcnt(10)
	s_waitcnt vmcnt(8)
	v_pk_fma_f32 v[64:65], v[72:73], s[10:11], v[64:65] op_sel_hi:[1,0,1]
	v_pk_fma_f32 v[62:63], v[70:71], s[10:11], v[62:63] op_sel_hi:[1,0,1]
	v_pk_fma_f32 v[36:37], v[96:97], s[10:11], v[36:37] op_sel_hi:[1,0,1]
	v_pk_fma_f32 v[34:35], v[94:95], s[10:11], v[34:35] op_sel_hi:[1,0,1]
	s_waitcnt vmcnt(6)
	s_waitcnt vmcnt(4)
	s_waitcnt vmcnt(3)
	s_waitcnt vmcnt(2)
	s_waitcnt vmcnt(1)
	s_waitcnt vmcnt(0)
	v_pk_fma_f32 v[60:61], v[68:69], s[10:11], v[60:61] op_sel_hi:[1,0,1]
	v_pk_fma_f32 v[58:59], v[66:67], s[10:11], v[58:59] op_sel_hi:[1,0,1]
	v_pk_fma_f32 v[48:49], v[80:81], s[10:11], v[48:49] op_sel_hi:[1,0,1]
	v_pk_fma_f32 v[46:47], v[78:79], s[10:11], v[46:47] op_sel_hi:[1,0,1]
	v_pk_fma_f32 v[44:45], v[76:77], s[10:11], v[44:45] op_sel_hi:[1,0,1]
	v_pk_fma_f32 v[42:43], v[74:75], s[10:11], v[42:43] op_sel_hi:[1,0,1]
	v_pk_fma_f32 v[56:57], v[88:89], s[10:11], v[56:57] op_sel_hi:[1,0,1]
	v_pk_fma_f32 v[54:55], v[86:87], s[10:11], v[54:55] op_sel_hi:[1,0,1]
	v_pk_fma_f32 v[52:53], v[84:85], s[10:11], v[52:53] op_sel_hi:[1,0,1]
	v_pk_fma_f32 v[50:51], v[82:83], s[10:11], v[50:51] op_sel_hi:[1,0,1]
	global_store_dwordx4 v[130:131], v[62:65], off
	global_store_dwordx4 v[130:131], v[58:61], off offset:16
	global_store_dwordx4 v[130:131], v[46:49], off offset:512
	global_store_dwordx4 v[130:131], v[42:45], off offset:528
	global_store_dwordx4 v[132:133], v[54:57], off
	global_store_dwordx4 v[132:133], v[50:53], off offset:16
	global_store_dwordx4 v[132:133], v[34:37], off offset:512
	v_pk_fma_f32 v[20:21], v[112:113], s[10:11], v[20:21] op_sel_hi:[1,0,1]
	v_pk_fma_f32 v[18:19], v[110:111], s[10:11], v[18:19] op_sel_hi:[1,0,1]
	v_lshl_add_u64 v[34:35], s[6:7], 0, v[158:159]
	v_lshl_add_u64 v[34:35], v[34:35], 0, v[146:147]
	v_pk_fma_f32 v[28:29], v[92:93], s[10:11], v[28:29] op_sel_hi:[1,0,1]
	v_pk_fma_f32 v[26:27], v[90:91], s[10:11], v[26:27] op_sel_hi:[1,0,1]
	global_store_dwordx4 v[34:35], v[18:21], off offset:512
	v_pk_fma_f32 v[12:13], v[108:109], s[10:11], v[12:13] op_sel_hi:[1,0,1]
	v_pk_fma_f32 v[10:11], v[106:107], s[10:11], v[10:11] op_sel_hi:[1,0,1]
	v_lshl_add_u64 v[18:19], s[6:7], 0, v[150:151]
	global_store_dwordx4 v[132:133], v[26:29], off offset:528
	global_store_dwordx4 v[34:35], v[10:13], off offset:528
	v_lshl_add_u64 v[18:19], v[18:19], 0, v[146:147]
	v_pk_fma_f32 v[28:29], v[104:105], s[10:11], v[40:41] op_sel_hi:[1,0,1]
	v_pk_fma_f32 v[26:27], v[102:103], s[10:11], v[38:39] op_sel_hi:[1,0,1]
	v_pk_fma_f32 v[12:13], v[116:117], s[10:11], v[24:25] op_sel_hi:[1,0,1]
	v_pk_fma_f32 v[10:11], v[114:115], s[10:11], v[22:23] op_sel_hi:[1,0,1]
	global_store_dwordx4 v[34:35], v[26:29], off
	global_store_dwordx4 v[18:19], v[10:13], off
	v_pk_fma_f32 v[8:9], v[124:125], s[10:11], v[8:9] op_sel_hi:[1,0,1]
	v_pk_fma_f32 v[28:29], v[100:101], s[10:11], v[32:33] op_sel_hi:[1,0,1]
	v_pk_fma_f32 v[26:27], v[98:99], s[10:11], v[30:31] op_sel_hi:[1,0,1]
	v_pk_fma_f32 v[12:13], v[120:121], s[10:11], v[16:17] op_sel_hi:[1,0,1]
	v_pk_fma_f32 v[10:11], v[118:119], s[10:11], v[14:15] op_sel_hi:[1,0,1]
	v_pk_fma_f32 v[6:7], v[122:123], s[10:11], v[6:7] op_sel_hi:[1,0,1]
	v_pk_fma_f32 v[4:5], v[128:129], s[10:11], v[4:5] op_sel_hi:[1,0,1]
	v_pk_fma_f32 v[2:3], v[126:127], s[10:11], v[2:3] op_sel_hi:[1,0,1]
	global_store_dwordx4 v[34:35], v[26:29], off offset:16
	global_store_dwordx4 v[18:19], v[10:13], off offset:16
	global_store_dwordx4 v[18:19], v[6:9], off offset:512
	global_store_dwordx4 v[18:19], v[2:5], off offset:528
	s_cbranch_vccnz .LBB0_1595
	s_andn2_b64 vcc, exec, s[4:5]
	s_cbranch_vccnz .LBB0_1594
	s_nop 0
	s_branch .LBB0_1594
